# P6 epilogue VALU trimmed: rstd of the 8 row groups up front, -log2e folded into a packed fma, packed +1
# speedup vs baseline: 1.0087x; 1.0028x over previous
; __device__ __forceinline__ u32x4 pack8(const float (&v)[8]) { u32x4 w; w.x = cvtpk(v[0], v[1]); w.y = cvtpk(v[2], v[3]); w.z = cvtpk(v[4], v[5]); w.w = cvtpk(v[6], v[7]); return w; }
; __device__ __forceinline__ float siluf_(float v) { return v * __builtin_amdgcn_rcpf(1.0f + __builtin_amdgcn_exp2f(-LOG2E * v)); }
; __device__ __forceinline__ float row_rstd(const float* SSQ, int row) {
;     const f32x4 v = *(const f32x4*)(SSQ + (size_t)row * 4);
;     return __builtin_amdgcn_rsqf(((v[0] + v[1]) + (v[2] + v[3])) * (1.0f / DM) + EPS);
; }
;     __device__ __forceinline__ void operator()(const pg8::f32x4 (&acc)[2][2][4][2], const pg8::Unit& u, int wr, int wc, int fr, int fq) const {
;         const int b = u.pm >> 4, c0 = u.pn * 128 + wc * 32 + 8 * fq; const float* bb = e.bias2 + (size_t)b * NUP + u.pn * 256 + wc * 32 + 8 * fq; float ba[8], bg[8];
; #pragma unroll
;         for (int h = 0; h < 2; ++h) { const f32x4 a = *(const f32x4*)(bb + 4 * h), g = *(const f32x4*)(bb + 128 + 4 * h);
; #pragma unroll
;             for (int i = 0; i < 4; ++i) { ba[4 * h + i] = a[i]; bg[4 * h + i] = g[i]; } }
; #pragma unroll
;         for (int ai = 0; ai < 2; ++ai)
; #pragma unroll
;             for (int m = 0; m < 4; ++m) { ACC8(va, ai, 0, m); ACC8(vb, ai, 1, m); const int row = u.pm * 256 + ai * 128 + wr * 64 + m * 16 + fr; const float rstd = row_rstd(SSQ, row); float o[8];
; #pragma unroll
;                 for (int i = 0; i < 8; ++i) o[i] = siluf_(rstd * va[i] + ba[i]) * (rstd * vb[i] + bg[i]);
;                 *(u32x4*)(e.ACT + (size_t)row * FF + c0) = pack8(o); }
;     }
.LBB9_773:
	v_lshl_add_u32 v164, s24, 8, v166
	v_ashrrev_i32_e32 v165, 31, v164
	s_ashr_i32 s2, s24, 4
	v_lshl_add_u64 v[88:89], v[164:165], 4, s[8:9]
	s_mul_hi_i32 s3, s2, 0x5800
	s_mulk_i32 s2, 0x5800
	global_load_dwordx4 v[174:177], v[88:89], off
	global_load_dwordx4 v[192:195], v[88:89], off offset:256
	global_load_dwordx4 v[196:199], v[88:89], off offset:512
	global_load_dwordx4 v[200:203], v[88:89], off offset:768
	global_load_dwordx4 v[210:213], v[88:89], off offset:2048
	global_load_dwordx4 v[214:217], v[88:89], off offset:2304
	global_load_dwordx4 v[218:221], v[88:89], off offset:2560
	global_load_dwordx4 v[238:241], v[88:89], off offset:2816
	s_add_u32 s17, s44, s2
	s_addc_u32 s19, s45, s3
	s_lshl_b32 s2, s54, 8
	s_ashr_i32 s3, s2, 31
	s_lshl_b64 s[2:3], s[2:3], 2
	s_add_u32 s2, s17, s2
	s_addc_u32 s3, s19, s3
	s_add_u32 s2, s2, s52
	s_addc_u32 s3, s3, 0
	global_load_dwordx4 v[96:99], v172, s[2:3]
	global_load_dwordx4 v[100:103], v172, s[2:3] offset:512
	global_load_dwordx4 v[88:91], v172, s[2:3] offset:16
	global_load_dwordx4 v[92:95], v172, s[2:3] offset:528
	v_lshl_or_b32 v162, s54, 7, v168
	v_mov_b64_e32 v[160:161], s[10:11]
	v_ashrrev_i32_e32 v163, 31, v162
	v_or_b32_e32 v180, 16, v164
	v_mad_i64_i32 v[178:179], s[2:3], v164, s53, v[160:161]
	v_lshlrev_b64 v[162:163], 1, v[162:163]
	v_ashrrev_i32_e32 v181, 31, v180
	s_andn2_b64 vcc, exec, s[0:1]
	s_mov_b64 s[0:1], -1
	s_waitcnt vmcnt(0)
	v_mul_f32_e32 v186, 0xbfb8aa3b, v96
	v_mul_f32_e32 v187, 0xbfb8aa3b, v97
	v_mul_f32_e32 v188, 0xbfb8aa3b, v98
	v_mul_f32_e32 v189, 0xbfb8aa3b, v99
	v_mul_f32_e32 v190, 0xbfb8aa3b, v88
	v_mul_f32_e32 v191, 0xbfb8aa3b, v89
	v_mul_f32_e32 v204, 0xbfb8aa3b, v90
	v_mul_f32_e32 v205, 0xbfb8aa3b, v91
	v_add_f32_e32 v174, v174, v175
	v_add_f32_e32 v176, v176, v177
	v_add_f32_e32 v174, v174, v176
	v_fmamk_f32 v174, v174, 0x3a800000, v173
	v_add_f32_e32 v192, v192, v193
	v_add_f32_e32 v194, v194, v195
	v_add_f32_e32 v192, v192, v194
	v_fmamk_f32 v192, v192, 0x3a800000, v173
	v_add_f32_e32 v196, v196, v197
	v_add_f32_e32 v198, v198, v199
	v_add_f32_e32 v196, v196, v198
	v_fmamk_f32 v196, v196, 0x3a800000, v173
	v_add_f32_e32 v200, v200, v201
	v_add_f32_e32 v202, v202, v203
	v_add_f32_e32 v200, v200, v202
	v_fmamk_f32 v200, v200, 0x3a800000, v173
	v_add_f32_e32 v210, v210, v211
	v_add_f32_e32 v212, v212, v213
	v_add_f32_e32 v210, v210, v212
	v_fmamk_f32 v210, v210, 0x3a800000, v173
	v_add_f32_e32 v214, v214, v215
	v_add_f32_e32 v216, v216, v217
	v_add_f32_e32 v214, v214, v216
	v_fmamk_f32 v214, v214, 0x3a800000, v173
	v_add_f32_e32 v218, v218, v219
	v_add_f32_e32 v220, v220, v221
	v_add_f32_e32 v218, v218, v220
	v_fmamk_f32 v218, v218, 0x3a800000, v173
	v_add_f32_e32 v238, v238, v239
	v_add_f32_e32 v240, v240, v241
	v_add_f32_e32 v238, v238, v240
	v_fmamk_f32 v238, v238, 0x3a800000, v173
	v_rsq_f32_e32 v242, v174
	v_rsq_f32_e32 v244, v192
	v_rsq_f32_e32 v246, v196
	v_rsq_f32_e32 v248, v200
	v_rsq_f32_e32 v178, v210
	v_rsq_f32_e32 v180, v214
	v_rsq_f32_e32 v182, v218
	v_rsq_f32_e32 v184, v238
	s_nop 0
	v_mul_f32_e32 v200, 0xbfb8aa3b, v242
	v_mov_b32_e32 v202, v164
	v_mad_i64_i32 v[210:211], s[2:3], v202, s53, v[160:161]
	v_pk_fma_f32 v[192:193], v[140:141], v[200:201], v[186:187] op_sel_hi:[1,0,1]
	v_pk_fma_f32 v[194:195], v[142:143], v[200:201], v[188:189] op_sel_hi:[1,0,1]
	v_pk_fma_f32 v[196:197], v[136:137], v[200:201], v[190:191] op_sel_hi:[1,0,1]
	v_pk_fma_f32 v[198:199], v[138:139], v[200:201], v[204:205] op_sel_hi:[1,0,1]
	v_pk_fma_f32 v[140:141], v[140:141], v[242:243], v[96:97] op_sel_hi:[1,0,1]
	v_pk_fma_f32 v[142:143], v[142:143], v[242:243], v[98:99] op_sel_hi:[1,0,1]
	v_pk_fma_f32 v[136:137], v[136:137], v[242:243], v[88:89] op_sel_hi:[1,0,1]
	v_pk_fma_f32 v[138:139], v[138:139], v[242:243], v[90:91] op_sel_hi:[1,0,1]
	v_exp_f32_e32 v192, v192
	v_exp_f32_e32 v193, v193
	v_exp_f32_e32 v194, v194
	v_exp_f32_e32 v195, v195
	v_exp_f32_e32 v196, v196
	v_exp_f32_e32 v197, v197
	v_exp_f32_e32 v198, v198
	v_exp_f32_e32 v199, v199
	v_pk_fma_f32 v[132:133], v[132:133], v[242:243], v[100:101] op_sel_hi:[1,0,1]
	v_pk_fma_f32 v[134:135], v[134:135], v[242:243], v[102:103] op_sel_hi:[1,0,1]
	v_pk_fma_f32 v[128:129], v[128:129], v[242:243], v[92:93] op_sel_hi:[1,0,1]
	v_pk_fma_f32 v[130:131], v[130:131], v[242:243], v[94:95] op_sel_hi:[1,0,1]
	v_pk_add_f32 v[192:193], v[192:193], 1.0 op_sel_hi:[1,0]
	v_pk_add_f32 v[194:195], v[194:195], 1.0 op_sel_hi:[1,0]
	v_pk_add_f32 v[196:197], v[196:197], 1.0 op_sel_hi:[1,0]
	v_pk_add_f32 v[198:199], v[198:199], 1.0 op_sel_hi:[1,0]
	v_rcp_f32_e32 v192, v192
	v_rcp_f32_e32 v193, v193
	v_rcp_f32_e32 v194, v194
	v_rcp_f32_e32 v195, v195
	v_rcp_f32_e32 v196, v196
	v_rcp_f32_e32 v197, v197
	v_rcp_f32_e32 v198, v198
	v_rcp_f32_e32 v199, v199
	v_lshl_add_u64 v[210:211], v[210:211], 0, v[162:163]
	v_pk_mul_f32 v[140:141], v[140:141], v[192:193]
	v_pk_mul_f32 v[142:143], v[142:143], v[194:195]
	v_pk_mul_f32 v[136:137], v[136:137], v[196:197]
	v_pk_mul_f32 v[138:139], v[138:139], v[198:199]
	v_pk_mul_f32 v[132:133], v[132:133], v[140:141]
	v_pk_mul_f32 v[134:135], v[134:135], v[142:143]
	v_pk_mul_f32 v[136:137], v[128:129], v[136:137]
	v_pk_mul_f32 v[138:139], v[130:131], v[138:139]
	v_cvt_pk_bf16_f32 v128, v132, v133
	v_cvt_pk_bf16_f32 v129, v134, v135
	v_cvt_pk_bf16_f32 v130, v136, v137
	v_cvt_pk_bf16_f32 v131, v138, v139
	global_store_dwordx4 v[210:211], v[128:131], off
	v_mul_f32_e32 v200, 0xbfb8aa3b, v244
	v_add_u32_e32 v202, 0x10, v164
	v_mad_i64_i32 v[210:211], s[2:3], v202, s53, v[160:161]
	v_pk_fma_f32 v[192:193], v[124:125], v[200:201], v[186:187] op_sel_hi:[1,0,1]
	v_pk_fma_f32 v[194:195], v[126:127], v[200:201], v[188:189] op_sel_hi:[1,0,1]
; __device__ __forceinline__ u32x4 pack8(const float (&v)[8]) { u32x4 w; w.x = cvtpk(v[0], v[1]); w.y = cvtpk(v[2], v[3]); w.z = cvtpk(v[4], v[5]); w.w = cvtpk(v[6], v[7]); return w; }
; __device__ __forceinline__ float siluf_(float v) { return v * __builtin_amdgcn_rcpf(1.0f + __builtin_amdgcn_exp2f(-LOG2E * v)); }
;     __device__ __forceinline__ void operator()(const pg8::f32x4 (&acc)[2][2][4][2], const pg8::Unit& u, int wr, int wc, int fr, int fq) const {
;         const int b = u.pm >> 4, c0 = u.pn * 128 + wc * 32 + 8 * fq; const float* bb = e.bias2 + (size_t)b * NUP + u.pn * 256 + wc * 32 + 8 * fq; float ba[8], bg[8];
; #pragma unroll
;         for (int h = 0; h < 2; ++h) { const f32x4 a = *(const f32x4*)(bb + 4 * h), g = *(const f32x4*)(bb + 128 + 4 * h);
; #pragma unroll
;             for (int i = 0; i < 4; ++i) { ba[4 * h + i] = a[i]; bg[4 * h + i] = g[i]; } }
; #pragma unroll
;         for (int ai = 0; ai < 2; ++ai)
; #pragma unroll
;             for (int m = 0; m < 4; ++m) { ACC8(va, ai, 0, m); ACC8(vb, ai, 1, m); const int row = u.pm * 256 + ai * 128 + wr * 64 + m * 16 + fr; const float rstd = row_rstd(SSQ, row); float o[8];
; #pragma unroll
;                 for (int i = 0; i < 8; ++i) o[i] = siluf_(rstd * va[i] + ba[i]) * (rstd * vb[i] + bg[i]);
;                 *(u32x4*)(e.ACT + (size_t)row * FF + c0) = pack8(o); }
;     }
	v_pk_fma_f32 v[196:197], v[120:121], v[200:201], v[190:191] op_sel_hi:[1,0,1]
	v_pk_fma_f32 v[198:199], v[122:123], v[200:201], v[204:205] op_sel_hi:[1,0,1]
	v_pk_fma_f32 v[124:125], v[124:125], v[244:245], v[96:97] op_sel_hi:[1,0,1]
	v_pk_fma_f32 v[126:127], v[126:127], v[244:245], v[98:99] op_sel_hi:[1,0,1]
	v_pk_fma_f32 v[120:121], v[120:121], v[244:245], v[88:89] op_sel_hi:[1,0,1]
	v_pk_fma_f32 v[122:123], v[122:123], v[244:245], v[90:91] op_sel_hi:[1,0,1]
	v_exp_f32_e32 v192, v192
	v_exp_f32_e32 v193, v193
	v_exp_f32_e32 v194, v194
	v_exp_f32_e32 v195, v195
	v_exp_f32_e32 v196, v196
	v_exp_f32_e32 v197, v197
	v_exp_f32_e32 v198, v198
	v_exp_f32_e32 v199, v199
	v_pk_fma_f32 v[116:117], v[116:117], v[244:245], v[100:101] op_sel_hi:[1,0,1]
	v_pk_fma_f32 v[118:119], v[118:119], v[244:245], v[102:103] op_sel_hi:[1,0,1]
	v_pk_fma_f32 v[112:113], v[112:113], v[244:245], v[92:93] op_sel_hi:[1,0,1]
	v_pk_fma_f32 v[114:115], v[114:115], v[244:245], v[94:95] op_sel_hi:[1,0,1]
	v_pk_add_f32 v[192:193], v[192:193], 1.0 op_sel_hi:[1,0]
	v_pk_add_f32 v[194:195], v[194:195], 1.0 op_sel_hi:[1,0]
	v_pk_add_f32 v[196:197], v[196:197], 1.0 op_sel_hi:[1,0]
	v_pk_add_f32 v[198:199], v[198:199], 1.0 op_sel_hi:[1,0]
	v_rcp_f32_e32 v192, v192
	v_rcp_f32_e32 v193, v193
	v_rcp_f32_e32 v194, v194
	v_rcp_f32_e32 v195, v195
	v_rcp_f32_e32 v196, v196
	v_rcp_f32_e32 v197, v197
	v_rcp_f32_e32 v198, v198
	v_rcp_f32_e32 v199, v199
	v_lshl_add_u64 v[210:211], v[210:211], 0, v[162:163]
	v_pk_mul_f32 v[124:125], v[124:125], v[192:193]
	v_pk_mul_f32 v[126:127], v[126:127], v[194:195]
	v_pk_mul_f32 v[120:121], v[120:121], v[196:197]
	v_pk_mul_f32 v[122:123], v[122:123], v[198:199]
	v_pk_mul_f32 v[116:117], v[116:117], v[124:125]
	v_pk_mul_f32 v[118:119], v[118:119], v[126:127]
	v_pk_mul_f32 v[120:121], v[112:113], v[120:121]
	v_pk_mul_f32 v[122:123], v[114:115], v[122:123]
	v_cvt_pk_bf16_f32 v112, v116, v117
	v_cvt_pk_bf16_f32 v113, v118, v119
	v_cvt_pk_bf16_f32 v114, v120, v121
	v_cvt_pk_bf16_f32 v115, v122, v123
	global_store_dwordx4 v[210:211], v[112:115], off
	v_mul_f32_e32 v200, 0xbfb8aa3b, v246
	v_add_u32_e32 v202, 0x20, v164
	v_mad_i64_i32 v[210:211], s[2:3], v202, s53, v[160:161]
	v_pk_fma_f32 v[192:193], v[108:109], v[200:201], v[186:187] op_sel_hi:[1,0,1]
	v_pk_fma_f32 v[194:195], v[110:111], v[200:201], v[188:189] op_sel_hi:[1,0,1]
	v_pk_fma_f32 v[196:197], v[104:105], v[200:201], v[190:191] op_sel_hi:[1,0,1]
	v_pk_fma_f32 v[198:199], v[106:107], v[200:201], v[204:205] op_sel_hi:[1,0,1]
	v_pk_fma_f32 v[108:109], v[108:109], v[246:247], v[96:97] op_sel_hi:[1,0,1]
	v_pk_fma_f32 v[110:111], v[110:111], v[246:247], v[98:99] op_sel_hi:[1,0,1]
	v_pk_fma_f32 v[104:105], v[104:105], v[246:247], v[88:89] op_sel_hi:[1,0,1]
	v_pk_fma_f32 v[106:107], v[106:107], v[246:247], v[90:91] op_sel_hi:[1,0,1]
	v_exp_f32_e32 v192, v192
	v_exp_f32_e32 v193, v193
	v_exp_f32_e32 v194, v194
	v_exp_f32_e32 v195, v195
	v_exp_f32_e32 v196, v196
	v_exp_f32_e32 v197, v197
	v_exp_f32_e32 v198, v198
	v_exp_f32_e32 v199, v199
	v_pk_fma_f32 v[84:85], v[84:85], v[246:247], v[100:101] op_sel_hi:[1,0,1]
	v_pk_fma_f32 v[86:87], v[86:87], v[246:247], v[102:103] op_sel_hi:[1,0,1]
	v_pk_fma_f32 v[80:81], v[80:81], v[246:247], v[92:93] op_sel_hi:[1,0,1]
	v_pk_fma_f32 v[82:83], v[82:83], v[246:247], v[94:95] op_sel_hi:[1,0,1]
	v_pk_add_f32 v[192:193], v[192:193], 1.0 op_sel_hi:[1,0]
	v_pk_add_f32 v[194:195], v[194:195], 1.0 op_sel_hi:[1,0]
	v_pk_add_f32 v[196:197], v[196:197], 1.0 op_sel_hi:[1,0]
	v_pk_add_f32 v[198:199], v[198:199], 1.0 op_sel_hi:[1,0]
	v_rcp_f32_e32 v192, v192
	v_rcp_f32_e32 v193, v193
	v_rcp_f32_e32 v194, v194
	v_rcp_f32_e32 v195, v195
	v_rcp_f32_e32 v196, v196
	v_rcp_f32_e32 v197, v197
	v_rcp_f32_e32 v198, v198
	v_rcp_f32_e32 v199, v199
	v_lshl_add_u64 v[210:211], v[210:211], 0, v[162:163]
	v_pk_mul_f32 v[108:109], v[108:109], v[192:193]
	v_pk_mul_f32 v[110:111], v[110:111], v[194:195]
	v_pk_mul_f32 v[104:105], v[104:105], v[196:197]
	v_pk_mul_f32 v[106:107], v[106:107], v[198:199]
	v_pk_mul_f32 v[84:85], v[84:85], v[108:109]
	v_pk_mul_f32 v[86:87], v[86:87], v[110:111]
	v_pk_mul_f32 v[104:105], v[80:81], v[104:105]
	v_pk_mul_f32 v[106:107], v[82:83], v[106:107]
	v_cvt_pk_bf16_f32 v80, v84, v85
	v_cvt_pk_bf16_f32 v81, v86, v87
	v_cvt_pk_bf16_f32 v82, v104, v105
	v_cvt_pk_bf16_f32 v83, v106, v107
	global_store_dwordx4 v[210:211], v[80:83], off
	v_mul_f32_e32 v200, 0xbfb8aa3b, v248
	v_add_u32_e32 v202, 0x30, v164
	v_mad_i64_i32 v[210:211], s[2:3], v202, s53, v[160:161]
	v_pk_fma_f32 v[192:193], v[76:77], v[200:201], v[186:187] op_sel_hi:[1,0,1]
	v_pk_fma_f32 v[194:195], v[78:79], v[200:201], v[188:189] op_sel_hi:[1,0,1]
	v_pk_fma_f32 v[196:197], v[72:73], v[200:201], v[190:191] op_sel_hi:[1,0,1]
	v_pk_fma_f32 v[198:199], v[74:75], v[200:201], v[204:205] op_sel_hi:[1,0,1]
	v_pk_fma_f32 v[76:77], v[76:77], v[248:249], v[96:97] op_sel_hi:[1,0,1]
	v_pk_fma_f32 v[78:79], v[78:79], v[248:249], v[98:99] op_sel_hi:[1,0,1]
	v_pk_fma_f32 v[72:73], v[72:73], v[248:249], v[88:89] op_sel_hi:[1,0,1]
	v_pk_fma_f32 v[74:75], v[74:75], v[248:249], v[90:91] op_sel_hi:[1,0,1]
	v_exp_f32_e32 v192, v192
	v_exp_f32_e32 v193, v193
	v_exp_f32_e32 v194, v194
	v_exp_f32_e32 v195, v195
	v_exp_f32_e32 v196, v196
	v_exp_f32_e32 v197, v197
	v_exp_f32_e32 v198, v198
	v_exp_f32_e32 v199, v199
	v_pk_fma_f32 v[68:69], v[68:69], v[248:249], v[100:101] op_sel_hi:[1,0,1]
	v_pk_fma_f32 v[70:71], v[70:71], v[248:249], v[102:103] op_sel_hi:[1,0,1]
	v_pk_fma_f32 v[64:65], v[64:65], v[248:249], v[92:93] op_sel_hi:[1,0,1]
	v_pk_fma_f32 v[66:67], v[66:67], v[248:249], v[94:95] op_sel_hi:[1,0,1]
	v_pk_add_f32 v[192:193], v[192:193], 1.0 op_sel_hi:[1,0]
; __device__ __forceinline__ u32x4 pack8(const float (&v)[8]) { u32x4 w; w.x = cvtpk(v[0], v[1]); w.y = cvtpk(v[2], v[3]); w.z = cvtpk(v[4], v[5]); w.w = cvtpk(v[6], v[7]); return w; }
; __device__ __forceinline__ float siluf_(float v) { return v * __builtin_amdgcn_rcpf(1.0f + __builtin_amdgcn_exp2f(-LOG2E * v)); }
;     __device__ __forceinline__ void operator()(const pg8::f32x4 (&acc)[2][2][4][2], const pg8::Unit& u, int wr, int wc, int fr, int fq) const {
;         const int b = u.pm >> 4, c0 = u.pn * 128 + wc * 32 + 8 * fq; const float* bb = e.bias2 + (size_t)b * NUP + u.pn * 256 + wc * 32 + 8 * fq; float ba[8], bg[8];
; #pragma unroll
;         for (int h = 0; h < 2; ++h) { const f32x4 a = *(const f32x4*)(bb + 4 * h), g = *(const f32x4*)(bb + 128 + 4 * h);
; #pragma unroll
;             for (int i = 0; i < 4; ++i) { ba[4 * h + i] = a[i]; bg[4 * h + i] = g[i]; } }
; #pragma unroll
;         for (int ai = 0; ai < 2; ++ai)
; #pragma unroll
;             for (int m = 0; m < 4; ++m) { ACC8(va, ai, 0, m); ACC8(vb, ai, 1, m); const int row = u.pm * 256 + ai * 128 + wr * 64 + m * 16 + fr; const float rstd = row_rstd(SSQ, row); float o[8];
; #pragma unroll
;                 for (int i = 0; i < 8; ++i) o[i] = siluf_(rstd * va[i] + ba[i]) * (rstd * vb[i] + bg[i]);
;                 *(u32x4*)(e.ACT + (size_t)row * FF + c0) = pack8(o); }
;     }
	v_pk_add_f32 v[194:195], v[194:195], 1.0 op_sel_hi:[1,0]
	v_pk_add_f32 v[196:197], v[196:197], 1.0 op_sel_hi:[1,0]
	v_pk_add_f32 v[198:199], v[198:199], 1.0 op_sel_hi:[1,0]
	v_rcp_f32_e32 v192, v192
	v_rcp_f32_e32 v193, v193
	v_rcp_f32_e32 v194, v194
	v_rcp_f32_e32 v195, v195
	v_rcp_f32_e32 v196, v196
	v_rcp_f32_e32 v197, v197
	v_rcp_f32_e32 v198, v198
	v_rcp_f32_e32 v199, v199
	v_lshl_add_u64 v[210:211], v[210:211], 0, v[162:163]
	v_pk_mul_f32 v[76:77], v[76:77], v[192:193]
	v_pk_mul_f32 v[78:79], v[78:79], v[194:195]
	v_pk_mul_f32 v[72:73], v[72:73], v[196:197]
	v_pk_mul_f32 v[74:75], v[74:75], v[198:199]
	v_pk_mul_f32 v[68:69], v[68:69], v[76:77]
	v_pk_mul_f32 v[70:71], v[70:71], v[78:79]
	v_pk_mul_f32 v[72:73], v[64:65], v[72:73]
	v_pk_mul_f32 v[74:75], v[66:67], v[74:75]
	v_cvt_pk_bf16_f32 v64, v68, v69
	v_cvt_pk_bf16_f32 v65, v70, v71
	v_cvt_pk_bf16_f32 v66, v72, v73
	v_cvt_pk_bf16_f32 v67, v74, v75
	global_store_dwordx4 v[210:211], v[64:67], off
	v_mul_f32_e32 v200, 0xbfb8aa3b, v178
	v_add_u32_e32 v202, 0x80, v164
	v_mad_i64_i32 v[210:211], s[2:3], v202, s53, v[160:161]
	v_pk_fma_f32 v[192:193], v[60:61], v[200:201], v[186:187] op_sel_hi:[1,0,1]
	v_pk_fma_f32 v[194:195], v[62:63], v[200:201], v[188:189] op_sel_hi:[1,0,1]
	v_pk_fma_f32 v[196:197], v[56:57], v[200:201], v[190:191] op_sel_hi:[1,0,1]
	v_pk_fma_f32 v[198:199], v[58:59], v[200:201], v[204:205] op_sel_hi:[1,0,1]
	v_pk_fma_f32 v[60:61], v[60:61], v[178:179], v[96:97] op_sel_hi:[1,0,1]
	v_pk_fma_f32 v[62:63], v[62:63], v[178:179], v[98:99] op_sel_hi:[1,0,1]
	v_pk_fma_f32 v[56:57], v[56:57], v[178:179], v[88:89] op_sel_hi:[1,0,1]
	v_pk_fma_f32 v[58:59], v[58:59], v[178:179], v[90:91] op_sel_hi:[1,0,1]
	v_exp_f32_e32 v192, v192
	v_exp_f32_e32 v193, v193
	v_exp_f32_e32 v194, v194
	v_exp_f32_e32 v195, v195
	v_exp_f32_e32 v196, v196
	v_exp_f32_e32 v197, v197
	v_exp_f32_e32 v198, v198
	v_exp_f32_e32 v199, v199
	v_pk_fma_f32 v[52:53], v[52:53], v[178:179], v[100:101] op_sel_hi:[1,0,1]
	v_pk_fma_f32 v[54:55], v[54:55], v[178:179], v[102:103] op_sel_hi:[1,0,1]
	v_pk_fma_f32 v[48:49], v[48:49], v[178:179], v[92:93] op_sel_hi:[1,0,1]
	v_pk_fma_f32 v[50:51], v[50:51], v[178:179], v[94:95] op_sel_hi:[1,0,1]
	v_pk_add_f32 v[192:193], v[192:193], 1.0 op_sel_hi:[1,0]
	v_pk_add_f32 v[194:195], v[194:195], 1.0 op_sel_hi:[1,0]
	v_pk_add_f32 v[196:197], v[196:197], 1.0 op_sel_hi:[1,0]
	v_pk_add_f32 v[198:199], v[198:199], 1.0 op_sel_hi:[1,0]
	v_rcp_f32_e32 v192, v192
	v_rcp_f32_e32 v193, v193
	v_rcp_f32_e32 v194, v194
	v_rcp_f32_e32 v195, v195
	v_rcp_f32_e32 v196, v196
	v_rcp_f32_e32 v197, v197
	v_rcp_f32_e32 v198, v198
	v_rcp_f32_e32 v199, v199
	v_lshl_add_u64 v[210:211], v[210:211], 0, v[162:163]
	v_pk_mul_f32 v[60:61], v[60:61], v[192:193]
	v_pk_mul_f32 v[62:63], v[62:63], v[194:195]
	v_pk_mul_f32 v[56:57], v[56:57], v[196:197]
	v_pk_mul_f32 v[58:59], v[58:59], v[198:199]
	v_pk_mul_f32 v[52:53], v[52:53], v[60:61]
	v_pk_mul_f32 v[54:55], v[54:55], v[62:63]
	v_pk_mul_f32 v[56:57], v[48:49], v[56:57]
	v_pk_mul_f32 v[58:59], v[50:51], v[58:59]
	v_cvt_pk_bf16_f32 v48, v52, v53
	v_cvt_pk_bf16_f32 v49, v54, v55
	v_cvt_pk_bf16_f32 v50, v56, v57
	v_cvt_pk_bf16_f32 v51, v58, v59
	global_store_dwordx4 v[210:211], v[48:51], off
	v_mul_f32_e32 v200, 0xbfb8aa3b, v180
	v_add_u32_e32 v202, 0x90, v164
	v_mad_i64_i32 v[210:211], s[2:3], v202, s53, v[160:161]
	v_pk_fma_f32 v[192:193], v[44:45], v[200:201], v[186:187] op_sel_hi:[1,0,1]
	v_pk_fma_f32 v[194:195], v[46:47], v[200:201], v[188:189] op_sel_hi:[1,0,1]
	v_pk_fma_f32 v[196:197], v[40:41], v[200:201], v[190:191] op_sel_hi:[1,0,1]
	v_pk_fma_f32 v[198:199], v[42:43], v[200:201], v[204:205] op_sel_hi:[1,0,1]
	v_pk_fma_f32 v[44:45], v[44:45], v[180:181], v[96:97] op_sel_hi:[1,0,1]
	v_pk_fma_f32 v[46:47], v[46:47], v[180:181], v[98:99] op_sel_hi:[1,0,1]
	v_pk_fma_f32 v[40:41], v[40:41], v[180:181], v[88:89] op_sel_hi:[1,0,1]
	v_pk_fma_f32 v[42:43], v[42:43], v[180:181], v[90:91] op_sel_hi:[1,0,1]
	v_exp_f32_e32 v192, v192
	v_exp_f32_e32 v193, v193
	v_exp_f32_e32 v194, v194
	v_exp_f32_e32 v195, v195
	v_exp_f32_e32 v196, v196
	v_exp_f32_e32 v197, v197
	v_exp_f32_e32 v198, v198
	v_exp_f32_e32 v199, v199
	v_pk_fma_f32 v[36:37], v[36:37], v[180:181], v[100:101] op_sel_hi:[1,0,1]
	v_pk_fma_f32 v[38:39], v[38:39], v[180:181], v[102:103] op_sel_hi:[1,0,1]
	v_pk_fma_f32 v[32:33], v[32:33], v[180:181], v[92:93] op_sel_hi:[1,0,1]
	v_pk_fma_f32 v[34:35], v[34:35], v[180:181], v[94:95] op_sel_hi:[1,0,1]
	v_pk_add_f32 v[192:193], v[192:193], 1.0 op_sel_hi:[1,0]
	v_pk_add_f32 v[194:195], v[194:195], 1.0 op_sel_hi:[1,0]
	v_pk_add_f32 v[196:197], v[196:197], 1.0 op_sel_hi:[1,0]
	v_pk_add_f32 v[198:199], v[198:199], 1.0 op_sel_hi:[1,0]
	v_rcp_f32_e32 v192, v192
	v_rcp_f32_e32 v193, v193
	v_rcp_f32_e32 v194, v194
	v_rcp_f32_e32 v195, v195
	v_rcp_f32_e32 v196, v196
	v_rcp_f32_e32 v197, v197
	v_rcp_f32_e32 v198, v198
	v_rcp_f32_e32 v199, v199
	v_lshl_add_u64 v[210:211], v[210:211], 0, v[162:163]
	v_pk_mul_f32 v[44:45], v[44:45], v[192:193]
	v_pk_mul_f32 v[46:47], v[46:47], v[194:195]
; __device__ __forceinline__ u32x4 pack8(const float (&v)[8]) { u32x4 w; w.x = cvtpk(v[0], v[1]); w.y = cvtpk(v[2], v[3]); w.z = cvtpk(v[4], v[5]); w.w = cvtpk(v[6], v[7]); return w; }
; __device__ __forceinline__ float siluf_(float v) { return v * __builtin_amdgcn_rcpf(1.0f + __builtin_amdgcn_exp2f(-LOG2E * v)); }
;     __device__ __forceinline__ void operator()(const pg8::f32x4 (&acc)[2][2][4][2], const pg8::Unit& u, int wr, int wc, int fr, int fq) const {
;         const int b = u.pm >> 4, c0 = u.pn * 128 + wc * 32 + 8 * fq; const float* bb = e.bias2 + (size_t)b * NUP + u.pn * 256 + wc * 32 + 8 * fq; float ba[8], bg[8];
; #pragma unroll
;         for (int h = 0; h < 2; ++h) { const f32x4 a = *(const f32x4*)(bb + 4 * h), g = *(const f32x4*)(bb + 128 + 4 * h);
; #pragma unroll
;             for (int i = 0; i < 4; ++i) { ba[4 * h + i] = a[i]; bg[4 * h + i] = g[i]; } }
; #pragma unroll
;         for (int ai = 0; ai < 2; ++ai)
; #pragma unroll
;             for (int m = 0; m < 4; ++m) { ACC8(va, ai, 0, m); ACC8(vb, ai, 1, m); const int row = u.pm * 256 + ai * 128 + wr * 64 + m * 16 + fr; const float rstd = row_rstd(SSQ, row); float o[8];
; #pragma unroll
;                 for (int i = 0; i < 8; ++i) o[i] = siluf_(rstd * va[i] + ba[i]) * (rstd * vb[i] + bg[i]);
;                 *(u32x4*)(e.ACT + (size_t)row * FF + c0) = pack8(o); }
;     }
	v_pk_mul_f32 v[40:41], v[40:41], v[196:197]
	v_pk_mul_f32 v[42:43], v[42:43], v[198:199]
	v_pk_mul_f32 v[36:37], v[36:37], v[44:45]
	v_pk_mul_f32 v[38:39], v[38:39], v[46:47]
	v_pk_mul_f32 v[40:41], v[32:33], v[40:41]
	v_pk_mul_f32 v[42:43], v[34:35], v[42:43]
	v_cvt_pk_bf16_f32 v32, v36, v37
	v_cvt_pk_bf16_f32 v33, v38, v39
	v_cvt_pk_bf16_f32 v34, v40, v41
	v_cvt_pk_bf16_f32 v35, v42, v43
	global_store_dwordx4 v[210:211], v[32:35], off
	v_mul_f32_e32 v200, 0xbfb8aa3b, v182
	v_add_u32_e32 v202, 0xa0, v164
	v_mad_i64_i32 v[210:211], s[2:3], v202, s53, v[160:161]
	v_pk_fma_f32 v[192:193], v[28:29], v[200:201], v[186:187] op_sel_hi:[1,0,1]
	v_pk_fma_f32 v[194:195], v[30:31], v[200:201], v[188:189] op_sel_hi:[1,0,1]
	v_pk_fma_f32 v[196:197], v[24:25], v[200:201], v[190:191] op_sel_hi:[1,0,1]
	v_pk_fma_f32 v[198:199], v[26:27], v[200:201], v[204:205] op_sel_hi:[1,0,1]
	v_pk_fma_f32 v[28:29], v[28:29], v[182:183], v[96:97] op_sel_hi:[1,0,1]
	v_pk_fma_f32 v[30:31], v[30:31], v[182:183], v[98:99] op_sel_hi:[1,0,1]
	v_pk_fma_f32 v[24:25], v[24:25], v[182:183], v[88:89] op_sel_hi:[1,0,1]
	v_pk_fma_f32 v[26:27], v[26:27], v[182:183], v[90:91] op_sel_hi:[1,0,1]
	v_exp_f32_e32 v192, v192
	v_exp_f32_e32 v193, v193
	v_exp_f32_e32 v194, v194
	v_exp_f32_e32 v195, v195
	v_exp_f32_e32 v196, v196
	v_exp_f32_e32 v197, v197
	v_exp_f32_e32 v198, v198
	v_exp_f32_e32 v199, v199
	v_pk_fma_f32 v[20:21], v[20:21], v[182:183], v[100:101] op_sel_hi:[1,0,1]
	v_pk_fma_f32 v[22:23], v[22:23], v[182:183], v[102:103] op_sel_hi:[1,0,1]
	v_pk_fma_f32 v[16:17], v[16:17], v[182:183], v[92:93] op_sel_hi:[1,0,1]
	v_pk_fma_f32 v[18:19], v[18:19], v[182:183], v[94:95] op_sel_hi:[1,0,1]
	v_pk_add_f32 v[192:193], v[192:193], 1.0 op_sel_hi:[1,0]
	v_pk_add_f32 v[194:195], v[194:195], 1.0 op_sel_hi:[1,0]
	v_pk_add_f32 v[196:197], v[196:197], 1.0 op_sel_hi:[1,0]
	v_pk_add_f32 v[198:199], v[198:199], 1.0 op_sel_hi:[1,0]
	v_rcp_f32_e32 v192, v192
	v_rcp_f32_e32 v193, v193
	v_rcp_f32_e32 v194, v194
	v_rcp_f32_e32 v195, v195
	v_rcp_f32_e32 v196, v196
	v_rcp_f32_e32 v197, v197
	v_rcp_f32_e32 v198, v198
	v_rcp_f32_e32 v199, v199
	v_lshl_add_u64 v[210:211], v[210:211], 0, v[162:163]
	v_pk_mul_f32 v[28:29], v[28:29], v[192:193]
	v_pk_mul_f32 v[30:31], v[30:31], v[194:195]
	v_pk_mul_f32 v[24:25], v[24:25], v[196:197]
	v_pk_mul_f32 v[26:27], v[26:27], v[198:199]
	v_pk_mul_f32 v[20:21], v[20:21], v[28:29]
	v_pk_mul_f32 v[22:23], v[22:23], v[30:31]
	v_pk_mul_f32 v[24:25], v[16:17], v[24:25]
	v_pk_mul_f32 v[26:27], v[18:19], v[26:27]
	v_cvt_pk_bf16_f32 v16, v20, v21
	v_cvt_pk_bf16_f32 v17, v22, v23
	v_cvt_pk_bf16_f32 v18, v24, v25
	v_cvt_pk_bf16_f32 v19, v26, v27
	global_store_dwordx4 v[210:211], v[16:19], off
	v_mul_f32_e32 v200, 0xbfb8aa3b, v184
	v_add_u32_e32 v202, 0xb0, v164
	v_mad_i64_i32 v[210:211], s[2:3], v202, s53, v[160:161]
	v_pk_fma_f32 v[192:193], v[12:13], v[200:201], v[186:187] op_sel_hi:[1,0,1]
	v_pk_fma_f32 v[194:195], v[14:15], v[200:201], v[188:189] op_sel_hi:[1,0,1]
	v_pk_fma_f32 v[196:197], v[8:9], v[200:201], v[190:191] op_sel_hi:[1,0,1]
	v_pk_fma_f32 v[198:199], v[10:11], v[200:201], v[204:205] op_sel_hi:[1,0,1]
	v_pk_fma_f32 v[12:13], v[12:13], v[184:185], v[96:97] op_sel_hi:[1,0,1]
	v_pk_fma_f32 v[14:15], v[14:15], v[184:185], v[98:99] op_sel_hi:[1,0,1]
	v_pk_fma_f32 v[8:9], v[8:9], v[184:185], v[88:89] op_sel_hi:[1,0,1]
	v_pk_fma_f32 v[10:11], v[10:11], v[184:185], v[90:91] op_sel_hi:[1,0,1]
	v_exp_f32_e32 v192, v192
	v_exp_f32_e32 v193, v193
	v_exp_f32_e32 v194, v194
	v_exp_f32_e32 v195, v195
	v_exp_f32_e32 v196, v196
	v_exp_f32_e32 v197, v197
	v_exp_f32_e32 v198, v198
	v_exp_f32_e32 v199, v199
	v_pk_fma_f32 v[4:5], v[4:5], v[184:185], v[100:101] op_sel_hi:[1,0,1]
	v_pk_fma_f32 v[6:7], v[6:7], v[184:185], v[102:103] op_sel_hi:[1,0,1]
	v_pk_fma_f32 v[0:1], v[0:1], v[184:185], v[92:93] op_sel_hi:[1,0,1]
	v_pk_fma_f32 v[2:3], v[2:3], v[184:185], v[94:95] op_sel_hi:[1,0,1]
	v_pk_add_f32 v[192:193], v[192:193], 1.0 op_sel_hi:[1,0]
	v_pk_add_f32 v[194:195], v[194:195], 1.0 op_sel_hi:[1,0]
	v_pk_add_f32 v[196:197], v[196:197], 1.0 op_sel_hi:[1,0]
	v_pk_add_f32 v[198:199], v[198:199], 1.0 op_sel_hi:[1,0]
	v_rcp_f32_e32 v192, v192
	v_rcp_f32_e32 v193, v193
	v_rcp_f32_e32 v194, v194
	v_rcp_f32_e32 v195, v195
	v_rcp_f32_e32 v196, v196
	v_rcp_f32_e32 v197, v197
	v_rcp_f32_e32 v198, v198
	v_rcp_f32_e32 v199, v199
	v_lshl_add_u64 v[210:211], v[210:211], 0, v[162:163]
	v_pk_mul_f32 v[12:13], v[12:13], v[192:193]
	v_pk_mul_f32 v[14:15], v[14:15], v[194:195]
	v_pk_mul_f32 v[8:9], v[8:9], v[196:197]
	v_pk_mul_f32 v[10:11], v[10:11], v[198:199]
	v_pk_mul_f32 v[4:5], v[4:5], v[12:13]
	v_pk_mul_f32 v[6:7], v[6:7], v[14:15]
	v_pk_mul_f32 v[8:9], v[0:1], v[8:9]
	v_pk_mul_f32 v[10:11], v[2:3], v[10:11]
	v_cvt_pk_bf16_f32 v0, v4, v5
	v_cvt_pk_bf16_f32 v1, v6, v7
	v_cvt_pk_bf16_f32 v2, v8, v9
	v_cvt_pk_bf16_f32 v3, v10, v11
	global_store_dwordx4 v[210:211], v[0:3], off
	s_cbranch_vccnz .LBB9_766
	s_andn2_b64 vcc, exec, s[6:7]
	s_cbranch_vccnz .LBB9_765
	s_barrier
	s_branch .LBB9_765
